# P1 in-projection epilogue rewritten by hand: per-wave LDS transpose of each 64x32 quadrant, row-contiguous 16-B-per-lane stores (bf16 copies and f32 K/V outputs)
# speedup vs baseline: 1.0080x; 1.0013x over previous
.LBB0_174:
	s_or_b64 exec, exec, s[4:5]
	v_and_b32_e32 v134, 63, v0
	v_lshrrev_b32_e32 v156, 6, v0
	v_and_b32_e32 v191, 15, v134
	v_lshrrev_b32_e32 v192, 4, v134
	v_readfirstlane_b32 s4, v156
	s_lshr_b32 s5, s4, 2
	s_and_b32 s6, s4, 3
	s_mul_i32 s7, s4, 0x2400
	s_add_i32 s7, s7, 16
	v_mul_u32_u24_e32 v175, 0x50, v191
	v_lshl_add_u32 v175, v192, 3, v175
	v_add_u32_e32 v175, s7, v175
	v_lshrrev_b32_e32 v156, 2, v134
	v_and_b32_e32 v157, 3, v134
	v_mul_u32_u24_e32 v176, 0x50, v156
	v_lshl_add_u32 v176, v157, 4, v176
	v_add_u32_e32 v176, s7, v176
	v_mul_u32_u24_e32 v177, 0x90, v191
	v_lshl_add_u32 v177, v192, 4, v177
	v_add_u32_e32 v177, s7, v177
	v_lshrrev_b32_e32 v193, 3, v134
	v_and_b32_e32 v194, 7, v134
	v_mul_u32_u24_e32 v178, 0x90, v193
	v_lshl_add_u32 v178, v194, 4, v178
	v_add_u32_e32 v178, s7, v178
	v_lshlrev_b32_e32 v183, 11, v193
	v_lshl_add_u32 v183, v194, 4, v183
	v_add_u32_e32 v184, 0x4000, v183
	v_add_u32_e32 v185, 0x8000, v183
	v_add_u32_e32 v186, 0xc000, v183
	v_add_u32_e32 v187, 0x10000, v183
	v_add_u32_e32 v188, 0x14000, v183
	v_add_u32_e32 v189, 0x18000, v183
	v_add_u32_e32 v190, 0x1c000, v183
	s_lshr_b32 s11, s0, 8
	s_mov_b32 s14, 10
	s_mov_b32 s30, 0
	s_mov_b32 s31, 0
	s_cmp_gt_u32 s11, 1
	s_cbranch_scc1 .Lp1e_t1
	s_mov_b64 s[12:13], s[56:57]
	s_mov_b32 s15, 0
	s_branch .Lp1e_tdone
.Lp1e_t1:
	s_cmp_gt_u32 s11, 5
	s_cbranch_scc1 .Lp1e_t2
	s_mov_b64 s[12:13], s[40:41]
	s_movk_i32 s15, 0x200
	s_mov_b32 s14, 11
	s_branch .Lp1e_tdone
.Lp1e_t2:
	s_cmp_gt_u32 s11, 7
	s_cbranch_scc1 .Lp1e_t3
	s_mov_b64 s[12:13], s[96:97]
	s_movk_i32 s15, 0x600
	s_mov_b32 s31, 1
	s_branch .Lp1e_tdone
.Lp1e_t3:
	s_mov_b32 s30, 1
	s_cmp_gt_u32 s11, 9
	s_cbranch_scc1 .Lp1e_t4
	v_readlane_b32 s12, v254, 23
	v_readlane_b32 s13, v254, 24
	s_movk_i32 s15, 0x800
	s_mov_b64 s[16:17], s[26:27]
	s_branch .Lp1e_tdone
.Lp1e_t4:
	v_readlane_b32 s12, v254, 25
	v_readlane_b32 s13, v254, 26
	s_movk_i32 s15, 0xa00
	s_mov_b64 s[16:17], s[22:23]
.Lp1e_tdone:
	s_lshl_b32 s6, s6, 5
	s_add_i32 s10, s0, s6
	s_sub_i32 s10, s10, s15
	s_lshl_b32 s6, s5, 6
	s_add_i32 s9, s8, s6
	v_lshlrev_b32_e32 v179, s14, v156
	v_lshl_add_u32 v179, v157, 4, v179
	s_lshl_b32 s64, 16, s14
	v_add_u32_e32 v180, s64, v179
	v_add_u32_e32 v181, s64, v180
	v_add_u32_e32 v182, s64, v181
	s_cmpk_lg_u32 s15, 0x200
	s_cbranch_scc1 .Lp1e_nosp
	s_and_b32 s64, s8, 0x1fff
	s_cmpk_lg_u32 s64, 0x1f00
	s_cbranch_scc1 .Lp1e_nosp
	s_cmp_lg_u32 s5, 1
	s_cbranch_scc1 .Lp1e_nosp
	s_lshr_b32 s0, s8, 13
	s_mul_i32 s0, s0, 0x3000
	s_lshl_b32 s1, s10, 2
	s_add_i32 s0, s0, s1
	s_add_u32 s0, s76, s0
	s_addc_u32 s1, s77, 0
	v_subrev_u32_e32 v193, 13, v191
	v_lshlrev_b32_e32 v193, 12, v193
	v_lshl_add_u32 v193, v192, 4, v193
	v_cmp_lt_u32_e32 vcc, 12, v191
	s_and_saveexec_b64 s[64:65], vcc
	global_store_dwordx4 v193, v[14:17], s[0:1]
	global_store_dwordx4 v193, v[10:13], s[0:1] offset:64
	global_store_dwordx4 v193, v[6:9], s[0:1] offset:512
	global_store_dwordx4 v193, v[2:5], s[0:1] offset:576
	s_mov_b64 exec, s[64:65]
.Lp1e_nosp:
	s_lshl_b32 s6, s9, s14
	s_lshl_b32 s7, s10, 1
	s_add_u32 s6, s6, s7
	s_add_u32 s12, s12, s6
	s_addc_u32 s13, s13, 0
	s_lshl_b32 s64, 128, s14
	s_add_u32 s4, s12, s64
	s_addc_u32 s5, s13, 0
	s_cmp_eq_u32 s30, 0
	s_cbranch_scc1 .Lp1e_nof32
	s_lshl_b32 s6, s9, 11
	s_lshl_b32 s7, s10, 2
	s_add_u32 s6, s6, s7
	s_add_u32 s16, s16, s6
	s_addc_u32 s17, s17, 0
	s_add_u32 s6, s16, 0x40000
	s_addc_u32 s7, s17, 0
.Lp1e_nof32:
	s_cmp_eq_u32 s30, 0
	s_cbranch_scc1 .Lp1e_b00
	ds_write_b128 v177, v[126:129]
	ds_write_b128 v177, v[122:125] offset:64
	ds_write_b128 v177, v[110:113] offset:2304
	ds_write_b128 v177, v[106:109] offset:2368
	ds_write_b128 v177, v[94:97] offset:4608
	ds_write_b128 v177, v[90:93] offset:4672
	ds_write_b128 v177, v[78:81] offset:6912
	ds_write_b128 v177, v[74:77] offset:6976
	s_waitcnt lgkmcnt(0)
	ds_read_b128 v[200:203], v178
	ds_read_b128 v[204:207], v178 offset:1152
	ds_read_b128 v[208:211], v178 offset:2304
	ds_read_b128 v[212:215], v178 offset:3456
	ds_read_b128 v[216:219], v178 offset:4608
	ds_read_b128 v[220:223], v178 offset:5760
	ds_read_b128 v[224:227], v178 offset:6912
	ds_read_b128 v[228:231], v178 offset:8064
	s_waitcnt lgkmcnt(0)
	global_store_dwordx4 v183, v[200:203], s[16:17]
	global_store_dwordx4 v184, v[204:207], s[16:17]
	global_store_dwordx4 v185, v[208:211], s[16:17]
	global_store_dwordx4 v186, v[212:215], s[16:17]
	global_store_dwordx4 v187, v[216:219], s[16:17]
	global_store_dwordx4 v188, v[220:223], s[16:17]
	global_store_dwordx4 v189, v[224:227], s[16:17]
	global_store_dwordx4 v190, v[228:231], s[16:17]
	s_branch .Lp1e_c00
.Lp1e_b00:
	s_cmp_eq_u32 s31, 0
	s_cbranch_scc1 .Lp1e_c00
	v_mul_f32_e32 v126, 0x3e38aa3b, v126
	v_mul_f32_e32 v127, 0x3e38aa3b, v127
	v_mul_f32_e32 v128, 0x3e38aa3b, v128
	v_mul_f32_e32 v129, 0x3e38aa3b, v129
	v_mul_f32_e32 v122, 0x3e38aa3b, v122
	v_mul_f32_e32 v123, 0x3e38aa3b, v123
	v_mul_f32_e32 v124, 0x3e38aa3b, v124
	v_mul_f32_e32 v125, 0x3e38aa3b, v125
	v_mul_f32_e32 v110, 0x3e38aa3b, v110
	v_mul_f32_e32 v111, 0x3e38aa3b, v111
	v_mul_f32_e32 v112, 0x3e38aa3b, v112
	v_mul_f32_e32 v113, 0x3e38aa3b, v113
	v_mul_f32_e32 v106, 0x3e38aa3b, v106
	v_mul_f32_e32 v107, 0x3e38aa3b, v107
	v_mul_f32_e32 v108, 0x3e38aa3b, v108
	v_mul_f32_e32 v109, 0x3e38aa3b, v109
	v_mul_f32_e32 v94, 0x3e38aa3b, v94
	v_mul_f32_e32 v95, 0x3e38aa3b, v95
	v_mul_f32_e32 v96, 0x3e38aa3b, v96
	v_mul_f32_e32 v97, 0x3e38aa3b, v97
	v_mul_f32_e32 v90, 0x3e38aa3b, v90
	v_mul_f32_e32 v91, 0x3e38aa3b, v91
	v_mul_f32_e32 v92, 0x3e38aa3b, v92
	v_mul_f32_e32 v93, 0x3e38aa3b, v93
	v_mul_f32_e32 v78, 0x3e38aa3b, v78
	v_mul_f32_e32 v79, 0x3e38aa3b, v79
	v_mul_f32_e32 v80, 0x3e38aa3b, v80
	v_mul_f32_e32 v81, 0x3e38aa3b, v81
	v_mul_f32_e32 v74, 0x3e38aa3b, v74
	v_mul_f32_e32 v75, 0x3e38aa3b, v75
	v_mul_f32_e32 v76, 0x3e38aa3b, v76
	v_mul_f32_e32 v77, 0x3e38aa3b, v77
.Lp1e_c00:
	v_cvt_pk_bf16_f32 v140, v126, v127
	v_cvt_pk_bf16_f32 v141, v128, v129
	ds_write_b64 v175, v[140:141]
	v_cvt_pk_bf16_f32 v142, v122, v123
	v_cvt_pk_bf16_f32 v143, v124, v125
	ds_write_b64 v175, v[142:143] offset:32
	v_cvt_pk_bf16_f32 v144, v110, v111
	v_cvt_pk_bf16_f32 v145, v112, v113
	ds_write_b64 v175, v[144:145] offset:1280
	v_cvt_pk_bf16_f32 v146, v106, v107
	v_cvt_pk_bf16_f32 v147, v108, v109
	ds_write_b64 v175, v[146:147] offset:1312
	v_cvt_pk_bf16_f32 v148, v94, v95
	v_cvt_pk_bf16_f32 v149, v96, v97
	ds_write_b64 v175, v[148:149] offset:2560
	v_cvt_pk_bf16_f32 v150, v90, v91
	v_cvt_pk_bf16_f32 v151, v92, v93
	ds_write_b64 v175, v[150:151] offset:2592
	v_cvt_pk_bf16_f32 v152, v78, v79
	v_cvt_pk_bf16_f32 v153, v80, v81
	ds_write_b64 v175, v[152:153] offset:3840
	v_cvt_pk_bf16_f32 v154, v74, v75
	v_cvt_pk_bf16_f32 v155, v76, v77
	ds_write_b64 v175, v[154:155] offset:3872
	s_waitcnt lgkmcnt(0)
	ds_read_b128 v[232:235], v176
	ds_read_b128 v[236:239], v176 offset:1280
	ds_read_b128 v[240:243], v176 offset:2560
	ds_read_b128 v[244:247], v176 offset:3840
	s_waitcnt lgkmcnt(0)
	global_store_dwordx4 v179, v[232:235], s[12:13]
	global_store_dwordx4 v180, v[236:239], s[12:13]
	global_store_dwordx4 v181, v[240:243], s[12:13]
	global_store_dwordx4 v182, v[244:247], s[12:13]
	s_cmp_eq_u32 s30, 0
	s_cbranch_scc1 .Lp1e_b01
	ds_write_b128 v177, v[118:121]
	ds_write_b128 v177, v[114:117] offset:64
	ds_write_b128 v177, v[102:105] offset:2304
	ds_write_b128 v177, v[98:101] offset:2368
	ds_write_b128 v177, v[86:89] offset:4608
	ds_write_b128 v177, v[82:85] offset:4672
	ds_write_b128 v177, v[70:73] offset:6912
	ds_write_b128 v177, v[66:69] offset:6976
	s_waitcnt lgkmcnt(0)
	ds_read_b128 v[200:203], v178
	ds_read_b128 v[204:207], v178 offset:1152
	ds_read_b128 v[208:211], v178 offset:2304
	ds_read_b128 v[212:215], v178 offset:3456
	ds_read_b128 v[216:219], v178 offset:4608
	ds_read_b128 v[220:223], v178 offset:5760
	ds_read_b128 v[224:227], v178 offset:6912
	ds_read_b128 v[228:231], v178 offset:8064
	s_waitcnt lgkmcnt(0)
	global_store_dwordx4 v183, v[200:203], s[16:17] offset:512
	global_store_dwordx4 v184, v[204:207], s[16:17] offset:512
	global_store_dwordx4 v185, v[208:211], s[16:17] offset:512
	global_store_dwordx4 v186, v[212:215], s[16:17] offset:512
	global_store_dwordx4 v187, v[216:219], s[16:17] offset:512
	global_store_dwordx4 v188, v[220:223], s[16:17] offset:512
	global_store_dwordx4 v189, v[224:227], s[16:17] offset:512
	global_store_dwordx4 v190, v[228:231], s[16:17] offset:512
	s_branch .Lp1e_c01
.Lp1e_b01:
	s_cmp_eq_u32 s31, 0
	s_cbranch_scc1 .Lp1e_c01
	v_mul_f32_e32 v118, 0x3e38aa3b, v118
	v_mul_f32_e32 v119, 0x3e38aa3b, v119
	v_mul_f32_e32 v120, 0x3e38aa3b, v120
	v_mul_f32_e32 v121, 0x3e38aa3b, v121
	v_mul_f32_e32 v114, 0x3e38aa3b, v114
	v_mul_f32_e32 v115, 0x3e38aa3b, v115
	v_mul_f32_e32 v116, 0x3e38aa3b, v116
	v_mul_f32_e32 v117, 0x3e38aa3b, v117
	v_mul_f32_e32 v102, 0x3e38aa3b, v102
	v_mul_f32_e32 v103, 0x3e38aa3b, v103
	v_mul_f32_e32 v104, 0x3e38aa3b, v104
	v_mul_f32_e32 v105, 0x3e38aa3b, v105
	v_mul_f32_e32 v98, 0x3e38aa3b, v98
	v_mul_f32_e32 v99, 0x3e38aa3b, v99
	v_mul_f32_e32 v100, 0x3e38aa3b, v100
	v_mul_f32_e32 v101, 0x3e38aa3b, v101
	v_mul_f32_e32 v86, 0x3e38aa3b, v86
	v_mul_f32_e32 v87, 0x3e38aa3b, v87
	v_mul_f32_e32 v88, 0x3e38aa3b, v88
	v_mul_f32_e32 v89, 0x3e38aa3b, v89
	v_mul_f32_e32 v82, 0x3e38aa3b, v82
	v_mul_f32_e32 v83, 0x3e38aa3b, v83
	v_mul_f32_e32 v84, 0x3e38aa3b, v84
	v_mul_f32_e32 v85, 0x3e38aa3b, v85
	v_mul_f32_e32 v70, 0x3e38aa3b, v70
	v_mul_f32_e32 v71, 0x3e38aa3b, v71
	v_mul_f32_e32 v72, 0x3e38aa3b, v72
	v_mul_f32_e32 v73, 0x3e38aa3b, v73
	v_mul_f32_e32 v66, 0x3e38aa3b, v66
	v_mul_f32_e32 v67, 0x3e38aa3b, v67
	v_mul_f32_e32 v68, 0x3e38aa3b, v68
	v_mul_f32_e32 v69, 0x3e38aa3b, v69
.Lp1e_c01:
	v_cvt_pk_bf16_f32 v140, v118, v119
	v_cvt_pk_bf16_f32 v141, v120, v121
	ds_write_b64 v175, v[140:141]
	v_cvt_pk_bf16_f32 v142, v114, v115
	v_cvt_pk_bf16_f32 v143, v116, v117
	ds_write_b64 v175, v[142:143] offset:32
	v_cvt_pk_bf16_f32 v144, v102, v103
	v_cvt_pk_bf16_f32 v145, v104, v105
	ds_write_b64 v175, v[144:145] offset:1280
	v_cvt_pk_bf16_f32 v146, v98, v99
	v_cvt_pk_bf16_f32 v147, v100, v101
	ds_write_b64 v175, v[146:147] offset:1312
	v_cvt_pk_bf16_f32 v148, v86, v87
	v_cvt_pk_bf16_f32 v149, v88, v89
	ds_write_b64 v175, v[148:149] offset:2560
	v_cvt_pk_bf16_f32 v150, v82, v83
	v_cvt_pk_bf16_f32 v151, v84, v85
	ds_write_b64 v175, v[150:151] offset:2592
	v_cvt_pk_bf16_f32 v152, v70, v71
	v_cvt_pk_bf16_f32 v153, v72, v73
	ds_write_b64 v175, v[152:153] offset:3840
	v_cvt_pk_bf16_f32 v154, v66, v67
	v_cvt_pk_bf16_f32 v155, v68, v69
	ds_write_b64 v175, v[154:155] offset:3872
	s_waitcnt lgkmcnt(0)
	ds_read_b128 v[232:235], v176
	ds_read_b128 v[236:239], v176 offset:1280
	ds_read_b128 v[240:243], v176 offset:2560
	ds_read_b128 v[244:247], v176 offset:3840
	s_waitcnt lgkmcnt(0)
	global_store_dwordx4 v179, v[232:235], s[12:13] offset:256
	global_store_dwordx4 v180, v[236:239], s[12:13] offset:256
	global_store_dwordx4 v181, v[240:243], s[12:13] offset:256
	global_store_dwordx4 v182, v[244:247], s[12:13] offset:256
	s_cmp_eq_u32 s30, 0
	s_cbranch_scc1 .Lp1e_b10
	ds_write_b128 v177, v[62:65]
	ds_write_b128 v177, v[58:61] offset:64
	ds_write_b128 v177, v[46:49] offset:2304
	ds_write_b128 v177, v[42:45] offset:2368
	ds_write_b128 v177, v[30:33] offset:4608
	ds_write_b128 v177, v[26:29] offset:4672
	ds_write_b128 v177, v[14:17] offset:6912
	ds_write_b128 v177, v[10:13] offset:6976
	s_waitcnt lgkmcnt(0)
	ds_read_b128 v[200:203], v178
	ds_read_b128 v[204:207], v178 offset:1152
	ds_read_b128 v[208:211], v178 offset:2304
	ds_read_b128 v[212:215], v178 offset:3456
	ds_read_b128 v[216:219], v178 offset:4608
	ds_read_b128 v[220:223], v178 offset:5760
	ds_read_b128 v[224:227], v178 offset:6912
	ds_read_b128 v[228:231], v178 offset:8064
	s_waitcnt lgkmcnt(0)
	global_store_dwordx4 v183, v[200:203], s[6:7]
	global_store_dwordx4 v184, v[204:207], s[6:7]
	global_store_dwordx4 v185, v[208:211], s[6:7]
	global_store_dwordx4 v186, v[212:215], s[6:7]
	global_store_dwordx4 v187, v[216:219], s[6:7]
	global_store_dwordx4 v188, v[220:223], s[6:7]
	global_store_dwordx4 v189, v[224:227], s[6:7]
	global_store_dwordx4 v190, v[228:231], s[6:7]
	s_branch .Lp1e_c10
.Lp1e_b10:
	s_cmp_eq_u32 s31, 0
	s_cbranch_scc1 .Lp1e_c10
	v_mul_f32_e32 v62, 0x3e38aa3b, v62
	v_mul_f32_e32 v63, 0x3e38aa3b, v63
	v_mul_f32_e32 v64, 0x3e38aa3b, v64
	v_mul_f32_e32 v65, 0x3e38aa3b, v65
	v_mul_f32_e32 v58, 0x3e38aa3b, v58
	v_mul_f32_e32 v59, 0x3e38aa3b, v59
	v_mul_f32_e32 v60, 0x3e38aa3b, v60
	v_mul_f32_e32 v61, 0x3e38aa3b, v61
	v_mul_f32_e32 v46, 0x3e38aa3b, v46
	v_mul_f32_e32 v47, 0x3e38aa3b, v47
	v_mul_f32_e32 v48, 0x3e38aa3b, v48
	v_mul_f32_e32 v49, 0x3e38aa3b, v49
	v_mul_f32_e32 v42, 0x3e38aa3b, v42
	v_mul_f32_e32 v43, 0x3e38aa3b, v43
	v_mul_f32_e32 v44, 0x3e38aa3b, v44
	v_mul_f32_e32 v45, 0x3e38aa3b, v45
	v_mul_f32_e32 v30, 0x3e38aa3b, v30
	v_mul_f32_e32 v31, 0x3e38aa3b, v31
	v_mul_f32_e32 v32, 0x3e38aa3b, v32
	v_mul_f32_e32 v33, 0x3e38aa3b, v33
	v_mul_f32_e32 v26, 0x3e38aa3b, v26
	v_mul_f32_e32 v27, 0x3e38aa3b, v27
	v_mul_f32_e32 v28, 0x3e38aa3b, v28
	v_mul_f32_e32 v29, 0x3e38aa3b, v29
	v_mul_f32_e32 v14, 0x3e38aa3b, v14
	v_mul_f32_e32 v15, 0x3e38aa3b, v15
	v_mul_f32_e32 v16, 0x3e38aa3b, v16
	v_mul_f32_e32 v17, 0x3e38aa3b, v17
	v_mul_f32_e32 v10, 0x3e38aa3b, v10
	v_mul_f32_e32 v11, 0x3e38aa3b, v11
	v_mul_f32_e32 v12, 0x3e38aa3b, v12
	v_mul_f32_e32 v13, 0x3e38aa3b, v13
.Lp1e_c10:
	v_cvt_pk_bf16_f32 v140, v62, v63
	v_cvt_pk_bf16_f32 v141, v64, v65
	ds_write_b64 v175, v[140:141]
	v_cvt_pk_bf16_f32 v142, v58, v59
	v_cvt_pk_bf16_f32 v143, v60, v61
	ds_write_b64 v175, v[142:143] offset:32
	v_cvt_pk_bf16_f32 v144, v46, v47
	v_cvt_pk_bf16_f32 v145, v48, v49
	ds_write_b64 v175, v[144:145] offset:1280
	v_cvt_pk_bf16_f32 v146, v42, v43
	v_cvt_pk_bf16_f32 v147, v44, v45
	ds_write_b64 v175, v[146:147] offset:1312
	v_cvt_pk_bf16_f32 v148, v30, v31
	v_cvt_pk_bf16_f32 v149, v32, v33
	ds_write_b64 v175, v[148:149] offset:2560
	v_cvt_pk_bf16_f32 v150, v26, v27
	v_cvt_pk_bf16_f32 v151, v28, v29
	ds_write_b64 v175, v[150:151] offset:2592
	v_cvt_pk_bf16_f32 v152, v14, v15
	v_cvt_pk_bf16_f32 v153, v16, v17
	ds_write_b64 v175, v[152:153] offset:3840
	v_cvt_pk_bf16_f32 v154, v10, v11
	v_cvt_pk_bf16_f32 v155, v12, v13
	ds_write_b64 v175, v[154:155] offset:3872
	s_waitcnt lgkmcnt(0)
	ds_read_b128 v[232:235], v176
	ds_read_b128 v[236:239], v176 offset:1280
	ds_read_b128 v[240:243], v176 offset:2560
	ds_read_b128 v[244:247], v176 offset:3840
	s_waitcnt lgkmcnt(0)
	global_store_dwordx4 v179, v[232:235], s[4:5]
	global_store_dwordx4 v180, v[236:239], s[4:5]
	global_store_dwordx4 v181, v[240:243], s[4:5]
	global_store_dwordx4 v182, v[244:247], s[4:5]
	s_cmp_eq_u32 s30, 0
	s_cbranch_scc1 .Lp1e_b11
	ds_write_b128 v177, v[54:57]
	ds_write_b128 v177, v[50:53] offset:64
	ds_write_b128 v177, v[38:41] offset:2304
	ds_write_b128 v177, v[34:37] offset:2368
	ds_write_b128 v177, v[22:25] offset:4608
	ds_write_b128 v177, v[18:21] offset:4672
	ds_write_b128 v177, v[6:9] offset:6912
	ds_write_b128 v177, v[2:5] offset:6976
	s_waitcnt lgkmcnt(0)
	ds_read_b128 v[200:203], v178
	ds_read_b128 v[204:207], v178 offset:1152
	ds_read_b128 v[208:211], v178 offset:2304
	ds_read_b128 v[212:215], v178 offset:3456
	ds_read_b128 v[216:219], v178 offset:4608
	ds_read_b128 v[220:223], v178 offset:5760
	ds_read_b128 v[224:227], v178 offset:6912
	ds_read_b128 v[228:231], v178 offset:8064
	s_waitcnt lgkmcnt(0)
	global_store_dwordx4 v183, v[200:203], s[6:7] offset:512
	global_store_dwordx4 v184, v[204:207], s[6:7] offset:512
	global_store_dwordx4 v185, v[208:211], s[6:7] offset:512
	global_store_dwordx4 v186, v[212:215], s[6:7] offset:512
	global_store_dwordx4 v187, v[216:219], s[6:7] offset:512
	global_store_dwordx4 v188, v[220:223], s[6:7] offset:512
	global_store_dwordx4 v189, v[224:227], s[6:7] offset:512
	global_store_dwordx4 v190, v[228:231], s[6:7] offset:512
	s_branch .Lp1e_c11
.Lp1e_b11:
	s_cmp_eq_u32 s31, 0
	s_cbranch_scc1 .Lp1e_c11
	v_mul_f32_e32 v54, 0x3e38aa3b, v54
	v_mul_f32_e32 v55, 0x3e38aa3b, v55
	v_mul_f32_e32 v56, 0x3e38aa3b, v56
	v_mul_f32_e32 v57, 0x3e38aa3b, v57
	v_mul_f32_e32 v50, 0x3e38aa3b, v50
	v_mul_f32_e32 v51, 0x3e38aa3b, v51
	v_mul_f32_e32 v52, 0x3e38aa3b, v52
	v_mul_f32_e32 v53, 0x3e38aa3b, v53
	v_mul_f32_e32 v38, 0x3e38aa3b, v38
	v_mul_f32_e32 v39, 0x3e38aa3b, v39
	v_mul_f32_e32 v40, 0x3e38aa3b, v40
	v_mul_f32_e32 v41, 0x3e38aa3b, v41
	v_mul_f32_e32 v34, 0x3e38aa3b, v34
	v_mul_f32_e32 v35, 0x3e38aa3b, v35
	v_mul_f32_e32 v36, 0x3e38aa3b, v36
	v_mul_f32_e32 v37, 0x3e38aa3b, v37
	v_mul_f32_e32 v22, 0x3e38aa3b, v22
	v_mul_f32_e32 v23, 0x3e38aa3b, v23
	v_mul_f32_e32 v24, 0x3e38aa3b, v24
	v_mul_f32_e32 v25, 0x3e38aa3b, v25
	v_mul_f32_e32 v18, 0x3e38aa3b, v18
	v_mul_f32_e32 v19, 0x3e38aa3b, v19
	v_mul_f32_e32 v20, 0x3e38aa3b, v20
	v_mul_f32_e32 v21, 0x3e38aa3b, v21
	v_mul_f32_e32 v6, 0x3e38aa3b, v6
	v_mul_f32_e32 v7, 0x3e38aa3b, v7
	v_mul_f32_e32 v8, 0x3e38aa3b, v8
	v_mul_f32_e32 v9, 0x3e38aa3b, v9
	v_mul_f32_e32 v2, 0x3e38aa3b, v2
	v_mul_f32_e32 v3, 0x3e38aa3b, v3
	v_mul_f32_e32 v4, 0x3e38aa3b, v4
	v_mul_f32_e32 v5, 0x3e38aa3b, v5
.Lp1e_c11:
	v_cvt_pk_bf16_f32 v140, v54, v55
	v_cvt_pk_bf16_f32 v141, v56, v57
	ds_write_b64 v175, v[140:141]
	v_cvt_pk_bf16_f32 v142, v50, v51
	v_cvt_pk_bf16_f32 v143, v52, v53
	ds_write_b64 v175, v[142:143] offset:32
	v_cvt_pk_bf16_f32 v144, v38, v39
	v_cvt_pk_bf16_f32 v145, v40, v41
	ds_write_b64 v175, v[144:145] offset:1280
	v_cvt_pk_bf16_f32 v146, v34, v35
	v_cvt_pk_bf16_f32 v147, v36, v37
	ds_write_b64 v175, v[146:147] offset:1312
	v_cvt_pk_bf16_f32 v148, v22, v23
	v_cvt_pk_bf16_f32 v149, v24, v25
	ds_write_b64 v175, v[148:149] offset:2560
	v_cvt_pk_bf16_f32 v150, v18, v19
	v_cvt_pk_bf16_f32 v151, v20, v21
	ds_write_b64 v175, v[150:151] offset:2592
	v_cvt_pk_bf16_f32 v152, v6, v7
	v_cvt_pk_bf16_f32 v153, v8, v9
	ds_write_b64 v175, v[152:153] offset:3840
	v_cvt_pk_bf16_f32 v154, v2, v3
	v_cvt_pk_bf16_f32 v155, v4, v5
	ds_write_b64 v175, v[154:155] offset:3872
	s_waitcnt lgkmcnt(0)
	ds_read_b128 v[232:235], v176
	ds_read_b128 v[236:239], v176 offset:1280
	ds_read_b128 v[240:243], v176 offset:2560
	ds_read_b128 v[244:247], v176 offset:3840
	s_waitcnt lgkmcnt(0)
	global_store_dwordx4 v179, v[232:235], s[4:5] offset:256
	global_store_dwordx4 v180, v[236:239], s[4:5] offset:256
	global_store_dwordx4 v181, v[240:243], s[4:5] offset:256
	global_store_dwordx4 v182, v[244:247], s[4:5] offset:256
	s_barrier
	s_branch .LBB0_167
